# priority reset to 0 for all waves at the end of every GEMM phase (clean priority state for the following phases)
# speedup vs baseline: 1.0094x; 1.0094x over previous
.LBB0_135:
	s_barrier
	s_setprio 0
	s_load_dwordx2 s[4:5], s[0:1], 0xa8
	s_waitcnt lgkmcnt(0)
	v_mov_b64_e32 v[144:145], s[4:5]

.LBB0_267:
	s_barrier
	s_setprio 0

.LBB0_805:
	s_barrier
	s_setprio 0
	s_load_dwordx2 s[4:5], s[0:1], 0xa8

.LBB0_897:
	s_barrier
	s_setprio 0
	s_load_dwordx2 s[26:27], s[0:1], 0xa8

.LBB0_1040:
	s_barrier
	s_setprio 0
	s_endpgm
